# v34 + dropped the epilogue vmcnt(0) that used to guard the (now hoisted) ssq loads in the four in-proj GEMMs, so the epilogue math overlaps the next tile's prefetch
# baseline (speedup 1.0000x reference)
.LBB0_118:
	s_lshl_b32 s19, s12, 8
	s_add_i32 s19, s19, s70
	v_or_b32_e32 v156, s19, v147
	v_ashrrev_i32_e32 v157, 31, v156
	v_lshl_add_u64 v[128:129], v[156:157], 2, s[16:17]
	v_mov_b32_e32 v144, v240
	v_or_b32_e32 v164, 16, v156
	v_ashrrev_i32_e32 v165, 31, v164
	v_or_b32_e32 v162, 32, v156
	v_or_b32_e32 v160, 48, v156
	v_lshl_add_u64 v[130:131], v[164:165], 2, s[16:17]
	v_ashrrev_i32_e32 v163, 31, v162
	v_ashrrev_i32_e32 v161, 31, v160
	v_lshl_add_u64 v[132:133], v[162:163], 2, s[16:17]
	v_lshl_add_u64 v[134:135], v[160:161], 2, s[16:17]
	v_mov_b32_e32 v178, v241
	v_mov_b32_e32 v177, v242
	v_mov_b32_e32 v176, v243
	v_mov_b32_e32 v165, v244
	v_mov_b32_e32 v163, v245
	v_mov_b32_e32 v161, v246
	v_mov_b32_e32 v157, v247
	s_cmp_lt_u32 s4, 16
	s_cselect_b64 s[12:13], -1, 0
	s_cmp_gt_u32 s4, 7
	s_cselect_b64 s[14:15], -1, 0
	s_and_b64 s[12:13], s[14:15], s[12:13]
	s_and_b64 s[12:13], s[12:13], exec
	s_cselect_b32 s5, 2, 1
	s_cmp_gt_i32 s4, 3
	s_cselect_b64 s[12:13], -1, 0
	s_and_b64 s[14:15], s[12:13], exec
	s_cselect_b32 s18, s5, 0
	s_cmp_gt_i32 s18, 1
	s_mov_b64 s[14:15], -1
	s_nop 0
	v_fmamk_f32 v128, v144, 0x3a000000, v175
	v_mul_f32_e32 v129, 0x4b800000, v128
	v_cmp_gt_f32_e32 vcc, s78, v128
	s_nop 1
	v_cndmask_b32_e32 v128, v128, v129, vcc
	v_rsq_f32_e32 v128, v128
	s_nop 0
	v_mul_f32_e32 v129, 0x45800000, v128
	v_cndmask_b32_e32 v168, v128, v129, vcc
	v_pk_mul_f32 v[126:127], v[126:127], v[168:169] op_sel_hi:[1,0]
	v_pk_mul_f32 v[124:125], v[124:125], v[168:169] op_sel_hi:[1,0]
	v_pk_mul_f32 v[122:123], v[122:123], v[168:169] op_sel_hi:[1,0]
	v_pk_mul_f32 v[120:121], v[120:121], v[168:169] op_sel_hi:[1,0]
	s_cbranch_scc0 .LBB0_120
	v_mul_f32_e32 v129, 0x3d372713, v120
	v_mul_f32_e32 v129, v120, v129
	v_mul_f32_e32 v130, 0x3d372713, v125
	v_fma_f32 v129, v120, v129, v120
	v_mul_f32_e32 v130, v125, v130
	v_mul_f32_e32 v129, 0x3f4c422a, v129
	v_fma_f32 v130, v125, v130, v125
	v_mul_f32_e32 v129, -2.0, v129
	v_mul_f32_e32 v130, 0x3f4c422a, v130
	v_mul_f32_e32 v129, 0x3fb8aa3b, v129
	v_mul_f32_e32 v130, -2.0, v130
	v_exp_f32_e32 v129, v129
	v_mul_f32_e32 v130, 0x3fb8aa3b, v130
	v_exp_f32_e32 v130, v130
	v_mul_f32_e32 v131, 0x3d372713, v126
	v_add_f32_e32 v129, 1.0, v129
	v_rcp_f32_e32 v158, v129
	v_add_f32_e32 v129, 1.0, v130
	v_mul_f32_e32 v130, 0x3d372713, v121
	v_mul_f32_e32 v132, 0x3d372713, v122
	v_mul_f32_e32 v130, v121, v130
	v_mul_f32_e32 v131, v126, v131
	v_mul_f32_e32 v132, v122, v132
	v_fma_f32 v130, v121, v130, v121
	v_fma_f32 v131, v126, v131, v126
	v_fma_f32 v132, v122, v132, v122
	v_mul_f32_e32 v130, 0x3f4c422a, v130
	v_mul_f32_e32 v131, 0x3f4c422a, v131
	v_mul_f32_e32 v132, 0x3f4c422a, v132
	v_mul_f32_e32 v130, -2.0, v130
	v_mul_f32_e32 v131, -2.0, v131
	v_mul_f32_e32 v132, -2.0, v132
	v_mul_f32_e32 v130, 0x3fb8aa3b, v130
	v_mul_f32_e32 v131, 0x3fb8aa3b, v131
	v_mul_f32_e32 v132, 0x3fb8aa3b, v132
	v_exp_f32_e32 v130, v130
	v_exp_f32_e32 v131, v131
	v_exp_f32_e32 v132, v132
	v_mul_f32_e32 v128, 0x3d372713, v124
	v_add_f32_e32 v133, 1.0, v130
	v_add_f32_e32 v130, 1.0, v131
	v_add_f32_e32 v131, 1.0, v132
	v_mul_f32_e32 v132, 0x3d372713, v127
	v_mul_f32_e32 v134, 0x3d372713, v123
	v_mul_f32_e32 v128, v124, v128
	v_mul_f32_e32 v132, v127, v132
	v_mul_f32_e32 v134, v123, v134
	v_fma_f32 v128, v124, v128, v124
	v_fma_f32 v132, v127, v132, v127
	v_fma_f32 v134, v123, v134, v123
	v_mul_f32_e32 v128, 0x3f4c422a, v128
	v_mul_f32_e32 v132, 0x3f4c422a, v132
	v_mul_f32_e32 v134, 0x3f4c422a, v134
	v_mul_f32_e32 v128, -2.0, v128
	v_mul_f32_e32 v132, -2.0, v132
	v_mul_f32_e32 v134, -2.0, v134
	v_mul_f32_e32 v128, 0x3fb8aa3b, v128
	v_mul_f32_e32 v132, 0x3fb8aa3b, v132
	v_mul_f32_e32 v134, 0x3fb8aa3b, v134
	v_exp_f32_e32 v128, v128
	v_exp_f32_e32 v132, v132
	v_exp_f32_e32 v134, v134
	v_rcp_f32_e32 v166, v131
	v_add_f32_e32 v128, 1.0, v128
	v_add_f32_e32 v131, 1.0, v132
	v_add_f32_e32 v132, 1.0, v134
	v_rcp_f32_e32 v128, v128
	v_rcp_f32_e32 v129, v129
	v_rcp_f32_e32 v130, v130
	v_rcp_f32_e32 v131, v131
	v_rcp_f32_e32 v167, v132
	v_rcp_f32_e32 v159, v133
	v_pk_mul_f32 v[132:133], v[124:125], v[128:129]
	v_pk_mul_f32 v[134:135], v[126:127], v[130:131]
	v_pk_mul_f32 v[130:131], v[122:123], v[166:167]
	v_pk_mul_f32 v[128:129], v[120:121], v[158:159]
	s_mov_b64 s[14:15], 0

.LBB0_609:
	s_nop 0
	v_fmamk_f32 v164, v164, 0x3a000000, v218
	v_mul_f32_e32 v165, 0x4b800000, v164
	v_cmp_gt_f32_e32 vcc, s83, v164
	s_cmp_eq_u32 s4, 3
	s_cselect_b64 s[4:5], -1, 0
	v_cndmask_b32_e32 v164, v164, v165, vcc
	v_rsq_f32_e32 v164, v164
	s_cmp_lt_u32 s8, 8
	s_cselect_b64 s[74:75], -1, 0
	s_mov_b64 s[6:7], -1
	v_mul_f32_e32 v165, 0x45800000, v164
	v_cndmask_b32_e32 v208, v164, v165, vcc
	v_cndmask_b32_e64 v164, 0, 1, s[4:5]
	v_pk_mul_f32 v[162:163], v[162:163], v[208:209] op_sel_hi:[1,0]
	v_pk_mul_f32 v[160:161], v[160:161], v[208:209] op_sel_hi:[1,0]
	v_pk_mul_f32 v[158:159], v[158:159], v[208:209] op_sel_hi:[1,0]
	v_pk_mul_f32 v[156:157], v[156:157], v[208:209] op_sel_hi:[1,0]
	s_and_b64 vcc, exec, s[12:13]
	v_cmp_ne_u32_e64 s[4:5], 1, v164
	s_cbranch_vccz .LBB0_613
	v_mov_b64_e32 v[166:167], v[158:159]
	v_mov_b64_e32 v[170:171], v[162:163]
	s_and_b64 vcc, exec, s[4:5]
	v_mov_b64_e32 v[164:165], v[156:157]
	v_mov_b64_e32 v[168:169], v[160:161]
	s_cbranch_vccnz .LBB0_612
	v_mul_f32_e32 v165, 0xbfb8aa3b, v156
	v_mul_f32_e32 v166, 0xbfb8aa3b, v161
	v_exp_f32_e32 v165, v165
	v_exp_f32_e32 v166, v166
	v_mul_f32_e32 v167, 0xbfb8aa3b, v162
	v_mul_f32_e32 v168, 0xbfb8aa3b, v158
	v_add_f32_e32 v165, 1.0, v165
	v_rcp_f32_e32 v200, v165
	v_add_f32_e32 v165, 1.0, v166
	v_mul_f32_e32 v166, 0xbfb8aa3b, v157
	v_exp_f32_e32 v166, v166
	v_exp_f32_e32 v167, v167
	v_exp_f32_e32 v168, v168
	v_mul_f32_e32 v164, 0xbfb8aa3b, v160
	v_add_f32_e32 v169, 1.0, v166
	v_add_f32_e32 v166, 1.0, v167
	v_add_f32_e32 v167, 1.0, v168
	v_mul_f32_e32 v168, 0xbfb8aa3b, v163
	v_mul_f32_e32 v170, 0xbfb8aa3b, v159
	v_exp_f32_e32 v164, v164
	v_exp_f32_e32 v168, v168
	v_exp_f32_e32 v170, v170
	v_rcp_f32_e32 v210, v167
	v_add_f32_e32 v164, 1.0, v164
	v_add_f32_e32 v167, 1.0, v168
	v_add_f32_e32 v168, 1.0, v170
	v_rcp_f32_e32 v164, v164
	v_rcp_f32_e32 v165, v165
	v_rcp_f32_e32 v166, v166
	v_rcp_f32_e32 v167, v167
	v_rcp_f32_e32 v211, v168
	v_rcp_f32_e32 v201, v169
	v_pk_mul_f32 v[168:169], v[160:161], v[164:165]
	v_pk_mul_f32 v[170:171], v[162:163], v[166:167]
	v_pk_mul_f32 v[166:167], v[158:159], v[210:211]
	v_pk_mul_f32 v[164:165], v[156:157], v[200:201]

.LBB0_1072:
	s_lshl_b32 s19, s12, 8
	s_add_i32 s19, s19, s68
	v_or_b32_e32 v156, s19, v147
	v_ashrrev_i32_e32 v157, 31, v156
	v_lshl_add_u64 v[128:129], v[156:157], 2, s[16:17]
	v_mov_b32_e32 v144, v240
	v_or_b32_e32 v164, 16, v156
	v_ashrrev_i32_e32 v165, 31, v164
	v_or_b32_e32 v162, 32, v156
	v_or_b32_e32 v160, 48, v156
	v_lshl_add_u64 v[130:131], v[164:165], 2, s[16:17]
	v_ashrrev_i32_e32 v163, 31, v162
	v_ashrrev_i32_e32 v161, 31, v160
	v_lshl_add_u64 v[132:133], v[162:163], 2, s[16:17]
	v_lshl_add_u64 v[134:135], v[160:161], 2, s[16:17]
	v_mov_b32_e32 v178, v241
	v_mov_b32_e32 v177, v242
	v_mov_b32_e32 v176, v243
	v_mov_b32_e32 v165, v244
	v_mov_b32_e32 v163, v245
	v_mov_b32_e32 v161, v246
	v_mov_b32_e32 v157, v247
	s_cmp_lt_u32 s4, 16
	s_cselect_b64 s[12:13], -1, 0
	s_cmp_gt_u32 s4, 7
	s_cselect_b64 s[14:15], -1, 0
	s_and_b64 s[12:13], s[14:15], s[12:13]
	s_and_b64 s[12:13], s[12:13], exec
	s_cselect_b32 s5, 2, 1
	s_cmp_gt_i32 s4, 3
	s_cselect_b64 s[12:13], -1, 0
	s_and_b64 s[14:15], s[12:13], exec
	s_cselect_b32 s18, s5, 0
	s_cmp_gt_i32 s18, 1
	s_mov_b64 s[14:15], -1
	s_nop 0
	v_fmamk_f32 v128, v144, 0x3a000000, v175
	v_mul_f32_e32 v129, 0x4b800000, v128
	v_cmp_gt_f32_e32 vcc, s76, v128
	s_nop 1
	v_cndmask_b32_e32 v128, v128, v129, vcc
	v_rsq_f32_e32 v128, v128
	s_nop 0
	v_mul_f32_e32 v129, 0x45800000, v128
	v_cndmask_b32_e32 v168, v128, v129, vcc
	v_pk_mul_f32 v[126:127], v[126:127], v[168:169] op_sel_hi:[1,0]
	v_pk_mul_f32 v[124:125], v[124:125], v[168:169] op_sel_hi:[1,0]
	v_pk_mul_f32 v[122:123], v[122:123], v[168:169] op_sel_hi:[1,0]
	v_pk_mul_f32 v[120:121], v[120:121], v[168:169] op_sel_hi:[1,0]
	s_cbranch_scc0 .LBB0_1074
	v_mul_f32_e32 v129, 0x3d372713, v120
	v_mul_f32_e32 v129, v120, v129
	v_mul_f32_e32 v130, 0x3d372713, v125
	v_fma_f32 v129, v120, v129, v120
	v_mul_f32_e32 v130, v125, v130
	v_mul_f32_e32 v129, 0x3f4c422a, v129
	v_fma_f32 v130, v125, v130, v125
	v_mul_f32_e32 v129, -2.0, v129
	v_mul_f32_e32 v130, 0x3f4c422a, v130
	v_mul_f32_e32 v129, 0x3fb8aa3b, v129
	v_mul_f32_e32 v130, -2.0, v130
	v_exp_f32_e32 v129, v129
	v_mul_f32_e32 v130, 0x3fb8aa3b, v130
	v_exp_f32_e32 v130, v130
	v_mul_f32_e32 v131, 0x3d372713, v126
	v_add_f32_e32 v129, 1.0, v129
	v_rcp_f32_e32 v158, v129
	v_add_f32_e32 v129, 1.0, v130
	v_mul_f32_e32 v130, 0x3d372713, v121
	v_mul_f32_e32 v132, 0x3d372713, v122
	v_mul_f32_e32 v130, v121, v130
	v_mul_f32_e32 v131, v126, v131
	v_mul_f32_e32 v132, v122, v132
	v_fma_f32 v130, v121, v130, v121
	v_fma_f32 v131, v126, v131, v126
	v_fma_f32 v132, v122, v132, v122
	v_mul_f32_e32 v130, 0x3f4c422a, v130
	v_mul_f32_e32 v131, 0x3f4c422a, v131
	v_mul_f32_e32 v132, 0x3f4c422a, v132
	v_mul_f32_e32 v130, -2.0, v130
	v_mul_f32_e32 v131, -2.0, v131
	v_mul_f32_e32 v132, -2.0, v132
	v_mul_f32_e32 v130, 0x3fb8aa3b, v130
	v_mul_f32_e32 v131, 0x3fb8aa3b, v131
	v_mul_f32_e32 v132, 0x3fb8aa3b, v132
	v_exp_f32_e32 v130, v130
	v_exp_f32_e32 v131, v131
	v_exp_f32_e32 v132, v132
	v_mul_f32_e32 v128, 0x3d372713, v124
	v_add_f32_e32 v133, 1.0, v130
	v_add_f32_e32 v130, 1.0, v131
	v_add_f32_e32 v131, 1.0, v132
	v_mul_f32_e32 v132, 0x3d372713, v127
	v_mul_f32_e32 v134, 0x3d372713, v123
	v_mul_f32_e32 v128, v124, v128
	v_mul_f32_e32 v132, v127, v132
	v_mul_f32_e32 v134, v123, v134
	v_fma_f32 v128, v124, v128, v124
	v_fma_f32 v132, v127, v132, v127
	v_fma_f32 v134, v123, v134, v123
	v_mul_f32_e32 v128, 0x3f4c422a, v128
	v_mul_f32_e32 v132, 0x3f4c422a, v132
	v_mul_f32_e32 v134, 0x3f4c422a, v134
	v_mul_f32_e32 v128, -2.0, v128
	v_mul_f32_e32 v132, -2.0, v132
	v_mul_f32_e32 v134, -2.0, v134
	v_mul_f32_e32 v128, 0x3fb8aa3b, v128
	v_mul_f32_e32 v132, 0x3fb8aa3b, v132
	v_mul_f32_e32 v134, 0x3fb8aa3b, v134
	v_exp_f32_e32 v128, v128
	v_exp_f32_e32 v132, v132
	v_exp_f32_e32 v134, v134
	v_rcp_f32_e32 v166, v131
	v_add_f32_e32 v128, 1.0, v128
	v_add_f32_e32 v131, 1.0, v132
	v_add_f32_e32 v132, 1.0, v134
	v_rcp_f32_e32 v128, v128
	v_rcp_f32_e32 v129, v129
	v_rcp_f32_e32 v130, v130
	v_rcp_f32_e32 v131, v131
	v_rcp_f32_e32 v167, v132
	v_rcp_f32_e32 v159, v133
	v_pk_mul_f32 v[132:133], v[124:125], v[128:129]
	v_pk_mul_f32 v[134:135], v[126:127], v[130:131]
	v_pk_mul_f32 v[130:131], v[122:123], v[166:167]
	v_pk_mul_f32 v[128:129], v[120:121], v[158:159]
	s_mov_b64 s[14:15], 0

.LBB0_1563:
	s_nop 0
	v_fmamk_f32 v164, v164, 0x3a000000, v218
	v_mul_f32_e32 v165, 0x4b800000, v164
	v_cmp_gt_f32_e32 vcc, s83, v164
	s_cmp_eq_u32 s4, 3
	s_cselect_b64 s[4:5], -1, 0
	v_cndmask_b32_e32 v164, v164, v165, vcc
	v_rsq_f32_e32 v164, v164
	s_cmp_lt_u32 s8, 8
	s_cselect_b64 s[68:69], -1, 0
	s_mov_b64 s[6:7], -1
	v_mul_f32_e32 v165, 0x45800000, v164
	v_cndmask_b32_e32 v208, v164, v165, vcc
	v_cndmask_b32_e64 v164, 0, 1, s[4:5]
	v_pk_mul_f32 v[162:163], v[162:163], v[208:209] op_sel_hi:[1,0]
	v_pk_mul_f32 v[160:161], v[160:161], v[208:209] op_sel_hi:[1,0]
	v_pk_mul_f32 v[158:159], v[158:159], v[208:209] op_sel_hi:[1,0]
	v_pk_mul_f32 v[156:157], v[156:157], v[208:209] op_sel_hi:[1,0]
	s_and_b64 vcc, exec, s[12:13]
	v_cmp_ne_u32_e64 s[4:5], 1, v164
	s_cbranch_vccz .LBB0_1567
	v_mov_b64_e32 v[166:167], v[158:159]
	v_mov_b64_e32 v[170:171], v[162:163]
	s_and_b64 vcc, exec, s[4:5]
	v_mov_b64_e32 v[164:165], v[156:157]
	v_mov_b64_e32 v[168:169], v[160:161]
	s_cbranch_vccnz .LBB0_1566
	v_mul_f32_e32 v165, 0xbfb8aa3b, v156
	v_mul_f32_e32 v166, 0xbfb8aa3b, v161
	v_exp_f32_e32 v165, v165
	v_exp_f32_e32 v166, v166
	v_mul_f32_e32 v167, 0xbfb8aa3b, v162
	v_mul_f32_e32 v168, 0xbfb8aa3b, v158
	v_add_f32_e32 v165, 1.0, v165
	v_rcp_f32_e32 v200, v165
	v_add_f32_e32 v165, 1.0, v166
	v_mul_f32_e32 v166, 0xbfb8aa3b, v157
	v_exp_f32_e32 v166, v166
	v_exp_f32_e32 v167, v167
	v_exp_f32_e32 v168, v168
	v_mul_f32_e32 v164, 0xbfb8aa3b, v160
	v_add_f32_e32 v169, 1.0, v166
	v_add_f32_e32 v166, 1.0, v167
	v_add_f32_e32 v167, 1.0, v168
	v_mul_f32_e32 v168, 0xbfb8aa3b, v163
	v_mul_f32_e32 v170, 0xbfb8aa3b, v159
	v_exp_f32_e32 v164, v164
	v_exp_f32_e32 v168, v168
	v_exp_f32_e32 v170, v170
	v_rcp_f32_e32 v210, v167
	v_add_f32_e32 v164, 1.0, v164
	v_add_f32_e32 v167, 1.0, v168
	v_add_f32_e32 v168, 1.0, v170
	v_rcp_f32_e32 v164, v164
	v_rcp_f32_e32 v165, v165
	v_rcp_f32_e32 v166, v166
	v_rcp_f32_e32 v167, v167
	v_rcp_f32_e32 v211, v168
	v_rcp_f32_e32 v201, v169
	v_pk_mul_f32 v[168:169], v[160:161], v[164:165]
	v_pk_mul_f32 v[170:171], v[162:163], v[166:167]
	v_pk_mul_f32 v[166:167], v[158:159], v[210:211]
	v_pk_mul_f32 v[164:165], v[156:157], v[200:201]
